# combined variant with phase-0a rebalancing cut-off moved from 6 to 4 items for workgroups 0-63
# baseline (speedup 1.0000x reference)
; DI int bidx() { int b = blockIdx.x; asm volatile("" : "+s"(b)); return b; }
; DI void phase0a(const Params& p, char* lds) {
;     ...
;   for (int it = bidx(); it < NITEMS; it += gridDim.x) {
;     if (it < N_SSM) { ssm_tables(p, it >> 1, it & 1, lds); continue; }
.LBB0_3:
	v_readlane_b32 s0, v254, 5
	v_readlane_b32 vcc_lo, v255, 52
	v_readlane_b32 s8, v254, 4
	s_nop 3
	s_cmpk_lg_u32 s0, 0x100
	s_cbranch_scc1 .Lp0_orig
	s_cmp_lg_u32 vcc_lo, 0
	s_cbranch_scc1 .Lp0_extra_next
	s_add_i32 s74, s74, s0
	s_mul_i32 s9, s0, 24
	s_add_i32 s34, s34, s9
	s_cmp_lt_u32 s8, 64
	s_cbranch_scc0 .Lp0_big
	s_cmpk_lt_i32 s74, 0x400
	s_cbranch_scc1 .LBB0_4
	s_branch .LBB0_90

; DI int bidx() { int b = blockIdx.x; asm volatile("" : "+s"(b)); return b; }
; DI void phase0a(const Params& p, char* lds) {
;     ...
;   for (int it = bidx(); it < NITEMS; it += gridDim.x) {
;     if (it < N_SSM) { ssm_tables(p, it >> 1, it & 1, lds); continue; }
.Lp0_extra_set:
	s_cmpk_lt_i32 vcc_lo, 0x380
	s_cbranch_scc0 .LBB0_90
	s_add_i32 s9, vcc_lo, 1
	v_writelane_b32 v255, s9, 52
	s_and_b32 s9, vcc_lo, 63
	s_lshr_b32 vcc_lo, vcc_lo, 6
	s_add_i32 vcc_lo, vcc_lo, 4
	s_lshl_b32 vcc_lo, vcc_lo, 8
	s_add_i32 s74, vcc_lo, s9
	s_branch .LBB0_4
